# attention row-max: two interleaved max3 chains and v_permlane32_swap for the cross-half max instead of an LDS bpermute round trip
# baseline (speedup 1.0000x reference)
; #define MX3(a, b, c) __builtin_fmaxf(__builtin_fmaxf((a), (b)), (c))
; __device__ __forceinline__ void attn_unit(const Params& P, unsigned char* lds, int h, int qb) {
;     ...
;             float mx = MX3(c0[0], c0[1], c1[0]);
;             mx = MX3(mx, c1[1], c0[2]);
; #pragma unroll
;             for (int r = 2; r < 16; r += 2) { mx = MX3(mx, c0[r], c0[r + 1]); mx = MX3(mx, c1[r], c1[r + 1]); }
;             mx = fmaxf(mx, __shfl_xor(mx, 32));
;             if (t == 0 || __any(mx > THR)) {
;                 const float dl = (t == 0) ? mx : fmaxf(mx, 0.f), f = __builtin_amdgcn_exp2f(-dl);
.LBB0_885:
	v_max3_f32 v2, v16, v17, v80
	v_max3_f32 v3, v81, v18, v19
	v_max3_f32 v2, v2, v82, v83
	v_max3_f32 v3, v3, v20, v21
	v_max3_f32 v2, v2, v84, v85
	v_max3_f32 v3, v3, v22, v23
	v_max3_f32 v2, v2, v86, v87
	v_max3_f32 v3, v3, v24, v25
	v_max3_f32 v2, v2, v88, v89
	v_max3_f32 v3, v3, v26, v27
	v_max3_f32 v2, v2, v90, v91
	v_max3_f32 v3, v3, v28, v29
	v_max3_f32 v2, v2, v92, v93
	v_max3_f32 v3, v3, v30, v31
	v_max3_f32 v2, v2, v94, v95
	v_max_f32_e32 v2, v2, v3
	v_mov_b32_e32 v3, v2
	v_mov_b32_e32 v4, v2
	s_cmp_eq_u32 s21, 0
	s_nop 0
	v_permlane32_swap_b32_e32 v3, v4
	v_max3_f32 v2, v2, v3, v4
	s_cbranch_scc1 .LBB0_888
	s_mov_b32 s10, 0x41000000
	v_cmp_lt_f32_e32 vcc, s10, v2
	s_cbranch_vccz .LBB0_890
	v_max_f32_e32 v2, v2, v2
	v_max_f32_e32 v2, 0, v2
